# strategy 2 prologue de-serialisation: hg_out q-row loads issued before the V^T barrier instead of after it
# speedup vs baseline: 1.0071x; 1.0071x over previous
; __device__ __forceinline__ float sigmoidf_(float x) { return 1.0f / (1.0f + __expf(-x)); }
; __device__ __forceinline__ void hg_bcum(const Params& p, int l, const u16* Uhg, int t0, int h, float* bc, float* lbs,
;                                         float* tots) {
;     ...
;   for (int k = 0; k < 4; ++k) {
;     const int s = (tid >> 4) + 16 * k, d0 = (tid & 15) * 8;
;     float z[8];
;     unpack8(*(const uint4*)(Uhg + (size_t)(t0 + s) * 2048 + 512 + h * 128 + d0), z);
;     float lf[8];
; #pragma unroll
;     for (int j = 0; j < 8; ++j) {
;       const float lbv = lbs[d0 + j];
;       const float f = lbv + (1.0f - lbv) * sigmoidf_(z[j]);
;       lf[j] = __logf(fmaxf(f, 1e-30f));
;     }
;     *(float4*)(bc + s * BCS + d0) = make_float4(lf[0], lf[1], lf[2], lf[3]);
;     *(float4*)(bc + s * BCS + d0 + 4) = make_float4(lf[4], lf[5], lf[6], lf[7]);
.LBB0_39:
	s_or_b64 exec, exec, s[0:1]
	s_and_b32 s12, s86, 0x7f
	s_lshl_b32 s0, s86, 4
	s_and_b32 s0, s0, 0xffffe000
	s_lshl_b32 s1, s12, 6
	s_or_b32 s13, s0, s1
	v_lshrrev_b32_e32 v59, 4, v34
	v_or_b32_e32 v46, s13, v59
	v_lshlrev_b32_e32 v34, 3, v50
	v_ashrrev_i32_e32 v47, 31, v46
	v_readlane_b32 s22, v252, 46
	v_and_b32_e32 v36, 0x78, v34
	v_lshlrev_b64 v[34:35], 12, v[46:47]
	v_readlane_b32 s23, v252, 47
	s_lshl_b32 s58, s20, 8
	v_lshlrev_b32_e32 v48, 1, v36
	v_lshl_add_u64 v[34:35], s[22:23], 0, v[34:35]
	v_lshl_add_u64 v[34:35], v[34:35], 0, s[58:59]
	v_mov_b32_e32 v49, v1
	v_lshl_add_u64 v[34:35], v[34:35], 0, v[48:49]
	s_waitcnt lgkmcnt(0)
	s_barrier
	v_lshl_add_u32 v64, v36, 2, s69
	s_mov_b32 s98, 0x10000
	s_mov_b32 s99, 0
	v_lshl_add_u64 v[110:111], v[34:35], 0, s[98:99]
	global_load_dwordx4 v[34:37], v[34:35], off offset:1024
	global_load_dwordx4 v[98:101], v[110:111], off offset:1024
	v_lshl_add_u64 v[110:111], v[110:111], 0, s[98:99]
	global_load_dwordx4 v[102:105], v[110:111], off offset:1024
	v_lshl_add_u64 v[110:111], v[110:111], 0, s[98:99]
	global_load_dwordx4 v[106:109], v[110:111], off offset:1024
	s_waitcnt vmcnt(3)
	v_lshlrev_b32_e32 v42, 16, v34
	v_mul_f32_e32 v42, 0xbfb8aa3b, v42
	v_exp_f32_e32 v42, v42
	v_and_b32_e32 v43, 0xffff0000, v34
	v_lshlrev_b32_e32 v44, 16, v35
	v_and_b32_e32 v45, 0xffff0000, v35
	v_add_f32_e32 v42, 1.0, v42
	v_div_scale_f32 v52, s[0:1], v42, v42, 1.0
	v_rcp_f32_e32 v53, v52
	v_lshlrev_b32_e32 v47, 16, v36
	v_and_b32_e32 v51, 0xffff0000, v36
	v_lshlrev_b32_e32 v62, 16, v37
	v_fma_f32 v54, -v52, v53, 1.0
	v_fmac_f32_e32 v53, v54, v53
	v_div_scale_f32 v54, vcc, 1.0, v42, 1.0
	v_mul_f32_e32 v55, v54, v53
	v_and_b32_e32 v63, 0xffff0000, v37
	ds_read_b128 v[38:41], v64 offset:33792
	ds_read_b128 v[34:37], v64 offset:33808
	v_fma_f32 v56, -v52, v55, v54
	v_fmac_f32_e32 v55, v56, v53
	v_fma_f32 v52, -v52, v55, v54
	v_div_fmas_f32 v52, v52, v53, v55
	s_waitcnt lgkmcnt(1)
	v_sub_f32_e32 v58, 1.0, v38
	v_div_fixup_f32 v42, v52, v42, 1.0
	v_fma_f32 v42, v58, v42, v38
	v_max_f32_e32 v42, 0xda24260, v42
	v_cmp_gt_f32_e32 vcc, s56, v42
	v_mul_f32_e32 v43, 0xbfb8aa3b, v43
	v_exp_f32_e32 v43, v43
	v_cndmask_b32_e64 v52, 0, 32, vcc
	v_ldexp_f32 v42, v42, v52
	v_log_f32_e32 v42, v42
	v_add_f32_e32 v43, 1.0, v43
	v_sub_f32_e32 v57, 1.0, v39
	v_mul_f32_e32 v44, 0xbfb8aa3b, v44
	v_mul_f32_e32 v52, 0x3f317217, v42
	v_fma_f32 v52, v42, s57, -v52
	v_fmac_f32_e32 v52, 0x3377d1cf, v42
	v_fmac_f32_e32 v52, 0x3f317217, v42
	v_cmp_lt_f32_e64 s[0:1], |v42|, s8
	v_exp_f32_e32 v44, v44
	v_mul_f32_e32 v45, 0xbfb8aa3b, v45
	v_cndmask_b32_e64 v42, v42, v52, s[0:1]
	v_cndmask_b32_e32 v52, 0, v201, vcc
	v_sub_f32_e32 v42, v42, v52
	v_div_scale_f32 v52, s[0:1], v43, v43, 1.0
	v_rcp_f32_e32 v53, v52
	v_add_f32_e32 v44, 1.0, v44
	v_exp_f32_e32 v45, v45
	v_mul_f32_e32 v47, 0xbfb8aa3b, v47
	v_fma_f32 v54, -v52, v53, 1.0
	v_fmac_f32_e32 v53, v54, v53
	v_div_scale_f32 v54, vcc, 1.0, v43, 1.0
	v_mul_f32_e32 v55, v54, v53
	v_fma_f32 v56, -v52, v55, v54
	v_fmac_f32_e32 v55, v56, v53
	v_fma_f32 v52, -v52, v55, v54
	v_div_fmas_f32 v52, v52, v53, v55
	v_div_fixup_f32 v43, v52, v43, 1.0
	v_fma_f32 v43, v43, v57, v39
	v_max_f32_e32 v43, 0xda24260, v43
	v_cmp_gt_f32_e32 vcc, s56, v43
	v_sub_f32_e32 v56, 1.0, v40
	v_add_f32_e32 v45, 1.0, v45
	v_cndmask_b32_e64 v52, 0, 32, vcc
	v_ldexp_f32 v43, v43, v52
	v_log_f32_e32 v43, v43
	v_exp_f32_e32 v47, v47
	v_mul_f32_e32 v52, 0x3f317217, v43
	v_fma_f32 v52, v43, s57, -v52
	v_fmac_f32_e32 v52, 0x3377d1cf, v43
	v_fmac_f32_e32 v52, 0x3f317217, v43
	v_cmp_lt_f32_e64 s[0:1], |v43|, s8
	v_add_f32_e32 v47, 1.0, v47
	s_nop 0
	v_cndmask_b32_e64 v43, v43, v52, s[0:1]
	v_cndmask_b32_e32 v52, 0, v201, vcc
	v_sub_f32_e32 v43, v43, v52
	v_div_scale_f32 v52, s[0:1], v44, v44, 1.0
	v_rcp_f32_e32 v53, v52
	s_nop 0
	v_fma_f32 v54, -v52, v53, 1.0
	v_fmac_f32_e32 v53, v54, v53
	v_div_scale_f32 v54, vcc, 1.0, v44, 1.0
	v_mul_f32_e32 v55, v54, v53
	v_fma_f32 v60, -v52, v55, v54
	v_fmac_f32_e32 v55, v60, v53
	v_fma_f32 v52, -v52, v55, v54
	v_div_fmas_f32 v52, v52, v53, v55
	v_div_fixup_f32 v44, v52, v44, 1.0
	v_fma_f32 v44, v44, v56, v40
	v_max_f32_e32 v44, 0xda24260, v44
	v_cmp_gt_f32_e32 vcc, s56, v44
	v_sub_f32_e32 v55, 1.0, v41
	s_nop 0
	v_cndmask_b32_e64 v52, 0, 32, vcc
	v_ldexp_f32 v44, v44, v52
	v_log_f32_e32 v44, v44
	s_nop 0
	v_mul_f32_e32 v52, 0x3f317217, v44
	v_fma_f32 v52, v44, s57, -v52
	v_fmac_f32_e32 v52, 0x3377d1cf, v44
	v_fmac_f32_e32 v52, 0x3f317217, v44
	v_cmp_lt_f32_e64 s[0:1], |v44|, s8
	s_nop 1
	v_cndmask_b32_e64 v44, v44, v52, s[0:1]
	v_cndmask_b32_e32 v52, 0, v201, vcc
	v_sub_f32_e32 v44, v44, v52
	v_div_scale_f32 v52, s[0:1], v45, v45, 1.0
	v_rcp_f32_e32 v53, v52
	s_nop 0
	v_fma_f32 v54, -v52, v53, 1.0
	v_fmac_f32_e32 v53, v54, v53
	v_div_scale_f32 v54, vcc, 1.0, v45, 1.0
	v_mul_f32_e32 v60, v54, v53
	v_fma_f32 v61, -v52, v60, v54
	v_fmac_f32_e32 v60, v61, v53
	v_fma_f32 v52, -v52, v60, v54
	v_div_fmas_f32 v52, v52, v53, v60
	v_div_fixup_f32 v45, v52, v45, 1.0
	v_fma_f32 v45, v45, v55, v41
	v_max_f32_e32 v45, 0xda24260, v45
	v_cmp_gt_f32_e32 vcc, s56, v45
	s_waitcnt lgkmcnt(0)
; __device__ __forceinline__ float sigmoidf_(float x) { return 1.0f / (1.0f + __expf(-x)); }
; __device__ __forceinline__ void hg_bcum(const Params& p, int l, const u16* Uhg, int t0, int h, float* bc, float* lbs,
;                                         float* tots) {
;     ...
;   for (int k = 0; k < 4; ++k) {
;     const int s = (tid >> 4) + 16 * k, d0 = (tid & 15) * 8;
;     float z[8];
;     unpack8(*(const uint4*)(Uhg + (size_t)(t0 + s) * 2048 + 512 + h * 128 + d0), z);
;     float lf[8];
; #pragma unroll
;     for (int j = 0; j < 8; ++j) {
;       const float lbv = lbs[d0 + j];
;       const float f = lbv + (1.0f - lbv) * sigmoidf_(z[j]);
;       lf[j] = __logf(fmaxf(f, 1e-30f));
;     }
;     *(float4*)(bc + s * BCS + d0) = make_float4(lf[0], lf[1], lf[2], lf[3]);
;     *(float4*)(bc + s * BCS + d0 + 4) = make_float4(lf[4], lf[5], lf[6], lf[7]);
	v_sub_f32_e32 v54, 1.0, v34
	v_cndmask_b32_e64 v52, 0, 32, vcc
	v_ldexp_f32 v45, v45, v52
	v_log_f32_e32 v45, v45
	s_nop 0
	v_mul_f32_e32 v52, 0x3f317217, v45
	v_fma_f32 v52, v45, s57, -v52
	v_fmac_f32_e32 v52, 0x3377d1cf, v45
	v_fmac_f32_e32 v52, 0x3f317217, v45
	v_cmp_lt_f32_e64 s[0:1], |v45|, s8
	s_nop 1
	v_cndmask_b32_e64 v45, v45, v52, s[0:1]
	v_cndmask_b32_e32 v52, 0, v201, vcc
	v_sub_f32_e32 v45, v45, v52
	v_div_scale_f32 v52, s[0:1], v47, v47, 1.0
	v_rcp_f32_e32 v53, v52
	s_nop 0
	v_fma_f32 v60, -v52, v53, 1.0
	v_fmac_f32_e32 v53, v60, v53
	v_div_scale_f32 v60, vcc, 1.0, v47, 1.0
	v_mul_f32_e32 v61, v60, v53
	v_fma_f32 v65, -v52, v61, v60
	v_fmac_f32_e32 v61, v65, v53
	v_fma_f32 v52, -v52, v61, v60
	v_div_fmas_f32 v52, v52, v53, v61
	v_div_fixup_f32 v47, v52, v47, 1.0
	v_fma_f32 v47, v47, v54, v34
	v_max_f32_e32 v47, 0xda24260, v47
	v_cmp_gt_f32_e32 vcc, s56, v47
	v_sub_f32_e32 v53, 1.0, v35
	s_nop 0
	v_cndmask_b32_e64 v52, 0, 32, vcc
	v_ldexp_f32 v47, v47, v52
	v_log_f32_e32 v47, v47
	s_nop 0
	v_mul_f32_e32 v52, 0x3f317217, v47
	v_fma_f32 v52, v47, s57, -v52
	v_fmac_f32_e32 v52, 0x3377d1cf, v47
	v_fmac_f32_e32 v52, 0x3f317217, v47
	v_cmp_lt_f32_e64 s[0:1], |v47|, s8
	s_nop 1
	v_cndmask_b32_e64 v47, v47, v52, s[0:1]
	v_cndmask_b32_e32 v52, 0, v201, vcc
	v_sub_f32_e32 v60, v47, v52
	v_mul_f32_e32 v47, 0xbfb8aa3b, v51
	v_exp_f32_e32 v47, v47
	s_nop 0
	v_add_f32_e32 v47, 1.0, v47
	v_div_scale_f32 v51, s[0:1], v47, v47, 1.0
	v_rcp_f32_e32 v52, v51
	s_nop 0
	v_fma_f32 v61, -v51, v52, 1.0
	v_fmac_f32_e32 v52, v61, v52
	v_div_scale_f32 v61, vcc, 1.0, v47, 1.0
	v_mul_f32_e32 v65, v61, v52
	v_fma_f32 v66, -v51, v65, v61
	v_fmac_f32_e32 v65, v66, v52
	v_fma_f32 v51, -v51, v65, v61
	v_div_fmas_f32 v51, v51, v52, v65
	v_div_fixup_f32 v47, v51, v47, 1.0
	v_fma_f32 v47, v47, v53, v35
	v_max_f32_e32 v47, 0xda24260, v47
	v_cmp_gt_f32_e32 vcc, s56, v47
	v_sub_f32_e32 v52, 1.0, v36
	s_nop 0
	v_cndmask_b32_e64 v51, 0, 32, vcc
	v_ldexp_f32 v47, v47, v51
	v_log_f32_e32 v47, v47
	s_nop 0
	v_mul_f32_e32 v51, 0x3f317217, v47
	v_fma_f32 v51, v47, s57, -v51
	v_fmac_f32_e32 v51, 0x3377d1cf, v47
	v_fmac_f32_e32 v51, 0x3f317217, v47
	v_cmp_lt_f32_e64 s[0:1], |v47|, s8
	s_nop 1
	v_cndmask_b32_e64 v47, v47, v51, s[0:1]
	v_cndmask_b32_e32 v51, 0, v201, vcc
	v_sub_f32_e32 v61, v47, v51
	v_mul_f32_e32 v47, 0xbfb8aa3b, v62
	v_exp_f32_e32 v47, v47
	s_nop 0
	v_add_f32_e32 v47, 1.0, v47
	v_div_scale_f32 v51, s[0:1], v47, v47, 1.0
	v_rcp_f32_e32 v62, v51
	s_nop 0
	v_fma_f32 v65, -v51, v62, 1.0
	v_fmac_f32_e32 v62, v65, v62
	v_div_scale_f32 v65, vcc, 1.0, v47, 1.0
	v_mul_f32_e32 v66, v65, v62
	v_fma_f32 v67, -v51, v66, v65
	v_fmac_f32_e32 v66, v67, v62
	v_fma_f32 v51, -v51, v66, v65
	v_div_fmas_f32 v51, v51, v62, v66
	v_div_fixup_f32 v47, v51, v47, 1.0
	v_fma_f32 v47, v47, v52, v36
	v_max_f32_e32 v47, 0xda24260, v47
	v_cmp_gt_f32_e32 vcc, s56, v47
	s_nop 1
	v_cndmask_b32_e64 v51, 0, 32, vcc
	v_ldexp_f32 v47, v47, v51
	v_log_f32_e32 v47, v47
	s_nop 0
	v_mul_f32_e32 v51, 0x3f317217, v47
	v_fma_f32 v51, v47, s57, -v51
	v_fmac_f32_e32 v51, 0x3377d1cf, v47
	v_fmac_f32_e32 v51, 0x3f317217, v47
	v_cmp_lt_f32_e64 s[0:1], |v47|, s8
	s_nop 1
	v_cndmask_b32_e64 v47, v47, v51, s[0:1]
	v_cndmask_b32_e32 v51, 0, v201, vcc
	v_sub_f32_e32 v62, v47, v51
	v_mul_f32_e32 v47, 0xbfb8aa3b, v63
	v_exp_f32_e32 v47, v47
	v_sub_f32_e32 v51, 1.0, v37
	v_add_f32_e32 v47, 1.0, v47
	v_div_scale_f32 v63, s[0:1], v47, v47, 1.0
	v_rcp_f32_e32 v65, v63
	s_nop 0
	v_fma_f32 v66, -v63, v65, 1.0
	v_fmac_f32_e32 v65, v66, v65
	v_div_scale_f32 v66, vcc, 1.0, v47, 1.0
	v_mul_f32_e32 v67, v66, v65
	v_fma_f32 v68, -v63, v67, v66
	v_fmac_f32_e32 v67, v68, v65
	v_fma_f32 v63, -v63, v67, v66
	v_div_fmas_f32 v63, v63, v65, v67
	v_div_fixup_f32 v47, v63, v47, 1.0
	v_fma_f32 v47, v47, v51, v37
	v_max_f32_e32 v47, 0xda24260, v47
	v_cmp_gt_f32_e32 vcc, s56, v47
	s_nop 1
	v_cndmask_b32_e64 v63, 0, 32, vcc
	v_ldexp_f32 v47, v47, v63
	v_log_f32_e32 v47, v47
	s_nop 0
	v_mul_f32_e32 v63, 0x3f317217, v47
	v_fma_f32 v63, v47, s57, -v63
	v_fmac_f32_e32 v63, 0x3377d1cf, v47
	v_fmac_f32_e32 v63, 0x3f317217, v47
	v_cmp_lt_f32_e64 s[0:1], |v47|, s8
	s_nop 1
	v_cndmask_b32_e64 v47, v47, v63, s[0:1]
	v_cndmask_b32_e32 v63, 0, v201, vcc
	v_sub_f32_e32 v63, v47, v63
	v_mad_u32_u24 v47, v59, s2, v64
	ds_write_b128 v47, v[42:45]
	ds_write_b128 v47, v[60:63] offset:16
	v_or_b32_e32 v42, 16, v46
	v_ashrrev_i32_e32 v43, 31, v42
	v_lshlrev_b64 v[42:43], 12, v[42:43]
	v_lshl_add_u64 v[42:43], s[22:23], 0, v[42:43]
	v_lshl_add_u64 v[42:43], v[42:43], 0, s[58:59]
	v_lshl_add_u64 v[42:43], v[42:43], 0, v[48:49]
	s_waitcnt vmcnt(2)
; __device__ __forceinline__ float sigmoidf_(float x) { return 1.0f / (1.0f + __expf(-x)); }
; __device__ __forceinline__ void hg_bcum(const Params& p, int l, const u16* Uhg, int t0, int h, float* bc, float* lbs,
;                                         float* tots) {
;     ...
;   for (int k = 0; k < 4; ++k) {
;     const int s = (tid >> 4) + 16 * k, d0 = (tid & 15) * 8;
;     float z[8];
;     unpack8(*(const uint4*)(Uhg + (size_t)(t0 + s) * 2048 + 512 + h * 128 + d0), z);
;     float lf[8];
; #pragma unroll
;     for (int j = 0; j < 8; ++j) {
;       const float lbv = lbs[d0 + j];
;       const float f = lbv + (1.0f - lbv) * sigmoidf_(z[j]);
;       lf[j] = __logf(fmaxf(f, 1e-30f));
;     }
;     *(float4*)(bc + s * BCS + d0) = make_float4(lf[0], lf[1], lf[2], lf[3]);
;     *(float4*)(bc + s * BCS + d0 + 4) = make_float4(lf[4], lf[5], lf[6], lf[7]);
	v_mov_b64_e32 v[42:43], v[98:99]
	v_mov_b64_e32 v[44:45], v[100:101]
	v_lshlrev_b32_e32 v61, 16, v42
	v_and_b32_e32 v62, 0xffff0000, v42
	v_mul_f32_e32 v42, 0xbfb8aa3b, v61
	v_exp_f32_e32 v42, v42
	v_lshlrev_b32_e32 v63, 16, v43
	v_and_b32_e32 v64, 0xffff0000, v43
	v_lshlrev_b32_e32 v65, 16, v44
	v_add_f32_e32 v42, 1.0, v42
	v_div_scale_f32 v43, s[0:1], v42, v42, 1.0
	v_and_b32_e32 v66, 0xffff0000, v44
	v_rcp_f32_e32 v44, v43
	v_lshlrev_b32_e32 v60, 16, v45
	v_and_b32_e32 v59, 0xffff0000, v45
	v_mul_f32_e32 v60, 0xbfb8aa3b, v60
	v_fma_f32 v45, -v43, v44, 1.0
	v_fmac_f32_e32 v44, v45, v44
	v_div_scale_f32 v45, vcc, 1.0, v42, 1.0
	v_mul_f32_e32 v61, v45, v44
	v_fma_f32 v67, -v43, v61, v45
	v_fmac_f32_e32 v61, v67, v44
	v_fma_f32 v43, -v43, v61, v45
	v_div_fmas_f32 v43, v43, v44, v61
	v_div_fixup_f32 v42, v43, v42, 1.0
	v_fma_f32 v42, v58, v42, v38
	v_max_f32_e32 v42, 0xda24260, v42
	v_cmp_gt_f32_e32 vcc, s56, v42
	v_exp_f32_e32 v60, v60
	v_mul_f32_e32 v59, 0xbfb8aa3b, v59
	v_cndmask_b32_e64 v43, 0, 32, vcc
	v_ldexp_f32 v42, v42, v43
	v_log_f32_e32 v42, v42
	v_add_f32_e32 v60, 1.0, v60
	v_exp_f32_e32 v59, v59
	v_mul_f32_e32 v43, 0x3f317217, v42
	v_fma_f32 v43, v42, s57, -v43
	v_fmac_f32_e32 v43, 0x3377d1cf, v42
	v_fmac_f32_e32 v43, 0x3f317217, v42
	v_cmp_lt_f32_e64 s[0:1], |v42|, s8
	v_add_f32_e32 v59, 1.0, v59
	s_nop 0
	v_cndmask_b32_e64 v42, v42, v43, s[0:1]
	v_cndmask_b32_e32 v43, 0, v201, vcc
	v_sub_f32_e32 v42, v42, v43
	v_mul_f32_e32 v43, 0xbfb8aa3b, v62
	v_exp_f32_e32 v43, v43
	s_nop 0
	v_add_f32_e32 v43, 1.0, v43
	v_div_scale_f32 v44, s[0:1], v43, v43, 1.0
	v_rcp_f32_e32 v45, v44
	s_nop 0
	v_fma_f32 v61, -v44, v45, 1.0
	v_fmac_f32_e32 v45, v61, v45
	v_div_scale_f32 v61, vcc, 1.0, v43, 1.0
	v_mul_f32_e32 v62, v61, v45
	v_fma_f32 v67, -v44, v62, v61
	v_fmac_f32_e32 v62, v67, v45
	v_fma_f32 v44, -v44, v62, v61
	v_div_fmas_f32 v44, v44, v45, v62
	v_div_fixup_f32 v43, v44, v43, 1.0
	v_fma_f32 v43, v57, v43, v39
	v_max_f32_e32 v43, 0xda24260, v43
	v_cmp_gt_f32_e32 vcc, s56, v43
	s_nop 1
	v_cndmask_b32_e64 v44, 0, 32, vcc
	v_ldexp_f32 v43, v43, v44
	v_log_f32_e32 v43, v43
	s_nop 0
	v_mul_f32_e32 v44, 0x3f317217, v43
	v_fma_f32 v44, v43, s57, -v44
	v_fmac_f32_e32 v44, 0x3377d1cf, v43
	v_fmac_f32_e32 v44, 0x3f317217, v43
	v_cmp_lt_f32_e64 s[0:1], |v43|, s8
	s_nop 1
	v_cndmask_b32_e64 v43, v43, v44, s[0:1]
	v_cndmask_b32_e32 v44, 0, v201, vcc
	v_sub_f32_e32 v43, v43, v44
	v_mul_f32_e32 v44, 0xbfb8aa3b, v63
	v_exp_f32_e32 v44, v44
	s_nop 0
	v_add_f32_e32 v44, 1.0, v44
	v_div_scale_f32 v45, s[0:1], v44, v44, 1.0
	v_rcp_f32_e32 v61, v45
	s_nop 0
	v_fma_f32 v62, -v45, v61, 1.0
	v_fmac_f32_e32 v61, v62, v61
	v_div_scale_f32 v62, vcc, 1.0, v44, 1.0
	v_mul_f32_e32 v63, v62, v61
	v_fma_f32 v67, -v45, v63, v62
	v_fmac_f32_e32 v63, v67, v61
	v_fma_f32 v45, -v45, v63, v62
	v_div_fmas_f32 v45, v45, v61, v63
	v_div_fixup_f32 v44, v45, v44, 1.0
	v_fma_f32 v44, v56, v44, v40
	v_max_f32_e32 v44, 0xda24260, v44
	v_cmp_gt_f32_e32 vcc, s56, v44
	s_nop 1
	v_cndmask_b32_e64 v45, 0, 32, vcc
	v_ldexp_f32 v44, v44, v45
	v_log_f32_e32 v44, v44
	s_nop 0
	v_mul_f32_e32 v45, 0x3f317217, v44
	v_fma_f32 v45, v44, s57, -v45
	v_fmac_f32_e32 v45, 0x3377d1cf, v44
	v_fmac_f32_e32 v45, 0x3f317217, v44
	v_cmp_lt_f32_e64 s[0:1], |v44|, s8
	s_nop 1
	v_cndmask_b32_e64 v44, v44, v45, s[0:1]
	v_cndmask_b32_e32 v45, 0, v201, vcc
	v_sub_f32_e32 v44, v44, v45
	v_mul_f32_e32 v45, 0xbfb8aa3b, v64
	v_exp_f32_e32 v45, v45
	s_nop 0
	v_add_f32_e32 v45, 1.0, v45
	v_div_scale_f32 v61, s[0:1], v45, v45, 1.0
	v_rcp_f32_e32 v62, v61
	s_nop 0
	v_fma_f32 v63, -v61, v62, 1.0
	v_fmac_f32_e32 v62, v63, v62
	v_div_scale_f32 v63, vcc, 1.0, v45, 1.0
	v_mul_f32_e32 v64, v63, v62
	v_fma_f32 v67, -v61, v64, v63
	v_fmac_f32_e32 v64, v67, v62
	v_fma_f32 v61, -v61, v64, v63
	v_div_fmas_f32 v61, v61, v62, v64
	v_div_fixup_f32 v45, v61, v45, 1.0
	v_fma_f32 v45, v55, v45, v41
	v_max_f32_e32 v45, 0xda24260, v45
	v_cmp_gt_f32_e32 vcc, s56, v45
	s_nop 1
	v_cndmask_b32_e64 v61, 0, 32, vcc
	v_ldexp_f32 v45, v45, v61
	v_log_f32_e32 v45, v45
	s_nop 0
	v_mul_f32_e32 v61, 0x3f317217, v45
	v_fma_f32 v61, v45, s57, -v61
	v_fmac_f32_e32 v61, 0x3377d1cf, v45
	v_fmac_f32_e32 v61, 0x3f317217, v45
	v_cmp_lt_f32_e64 s[0:1], |v45|, s8
	s_nop 1
	v_cndmask_b32_e64 v45, v45, v61, s[0:1]
	v_cndmask_b32_e32 v61, 0, v201, vcc
	v_sub_f32_e32 v45, v45, v61
	v_mul_f32_e32 v61, 0xbfb8aa3b, v65
	v_exp_f32_e32 v61, v61
	s_nop 0
	v_add_f32_e32 v61, 1.0, v61
	v_div_scale_f32 v62, s[0:1], v61, v61, 1.0
	v_rcp_f32_e32 v63, v62
	s_nop 0
	v_fma_f32 v64, -v62, v63, 1.0
	v_fmac_f32_e32 v63, v64, v63
	v_div_scale_f32 v64, vcc, 1.0, v61, 1.0
	v_mul_f32_e32 v65, v64, v63
	v_fma_f32 v67, -v62, v65, v64
	v_fmac_f32_e32 v65, v67, v63
	v_fma_f32 v62, -v62, v65, v64
	v_div_fmas_f32 v62, v62, v63, v65
	v_div_fixup_f32 v61, v62, v61, 1.0
	v_fma_f32 v61, v54, v61, v34
	v_max_f32_e32 v61, 0xda24260, v61
	v_cmp_gt_f32_e32 vcc, s56, v61
	s_nop 1
	v_cndmask_b32_e64 v62, 0, 32, vcc
	v_ldexp_f32 v61, v61, v62
	v_log_f32_e32 v61, v61
	s_nop 0
	v_mul_f32_e32 v62, 0x3f317217, v61
	v_fma_f32 v62, v61, s57, -v62
	v_fmac_f32_e32 v62, 0x3377d1cf, v61
	v_fmac_f32_e32 v62, 0x3f317217, v61
	v_cmp_lt_f32_e64 s[0:1], |v61|, s8
	s_nop 1
	v_cndmask_b32_e64 v61, v61, v62, s[0:1]
	v_cndmask_b32_e32 v62, 0, v201, vcc
	v_sub_f32_e32 v62, v61, v62
	v_mul_f32_e32 v61, 0xbfb8aa3b, v66
	v_exp_f32_e32 v61, v61
	s_nop 0
	v_add_f32_e32 v61, 1.0, v61
	v_div_scale_f32 v63, s[0:1], v61, v61, 1.0
	v_rcp_f32_e32 v64, v63
	s_nop 0
	v_fma_f32 v65, -v63, v64, 1.0
	v_fmac_f32_e32 v64, v65, v64
	v_div_scale_f32 v65, vcc, 1.0, v61, 1.0
	v_mul_f32_e32 v66, v65, v64
	v_fma_f32 v67, -v63, v66, v65
; __device__ __forceinline__ float sigmoidf_(float x) { return 1.0f / (1.0f + __expf(-x)); }
; __device__ __forceinline__ void hg_bcum(const Params& p, int l, const u16* Uhg, int t0, int h, float* bc, float* lbs,
;                                         float* tots) {
;     ...
;   for (int k = 0; k < 4; ++k) {
;     const int s = (tid >> 4) + 16 * k, d0 = (tid & 15) * 8;
;     float z[8];
;     unpack8(*(const uint4*)(Uhg + (size_t)(t0 + s) * 2048 + 512 + h * 128 + d0), z);
;     float lf[8];
; #pragma unroll
;     for (int j = 0; j < 8; ++j) {
;       const float lbv = lbs[d0 + j];
;       const float f = lbv + (1.0f - lbv) * sigmoidf_(z[j]);
;       lf[j] = __logf(fmaxf(f, 1e-30f));
;     }
;     *(float4*)(bc + s * BCS + d0) = make_float4(lf[0], lf[1], lf[2], lf[3]);
;     *(float4*)(bc + s * BCS + d0 + 4) = make_float4(lf[4], lf[5], lf[6], lf[7]);
	v_fmac_f32_e32 v66, v67, v64
	v_fma_f32 v63, -v63, v66, v65
	v_div_fmas_f32 v63, v63, v64, v66
	v_div_fixup_f32 v61, v63, v61, 1.0
	v_fma_f32 v61, v53, v61, v35
	v_max_f32_e32 v61, 0xda24260, v61
	v_cmp_gt_f32_e32 vcc, s56, v61
	s_nop 1
	v_cndmask_b32_e64 v63, 0, 32, vcc
	v_ldexp_f32 v61, v61, v63
	v_log_f32_e32 v61, v61
	s_nop 0
	v_mul_f32_e32 v63, 0x3f317217, v61
	v_fma_f32 v63, v61, s57, -v63
	v_fmac_f32_e32 v63, 0x3377d1cf, v61
	v_fmac_f32_e32 v63, 0x3f317217, v61
	v_cmp_lt_f32_e64 s[0:1], |v61|, s8
	s_nop 1
	v_cndmask_b32_e64 v61, v61, v63, s[0:1]
	v_cndmask_b32_e32 v63, 0, v201, vcc
	v_sub_f32_e32 v63, v61, v63
	v_div_scale_f32 v61, s[0:1], v60, v60, 1.0
	v_rcp_f32_e32 v64, v61
	s_nop 0
	v_fma_f32 v65, -v61, v64, 1.0
	v_fmac_f32_e32 v64, v65, v64
	v_div_scale_f32 v65, vcc, 1.0, v60, 1.0
	v_mul_f32_e32 v66, v65, v64
	v_fma_f32 v67, -v61, v66, v65
	v_fmac_f32_e32 v66, v67, v64
	v_fma_f32 v61, -v61, v66, v65
	v_div_fmas_f32 v61, v61, v64, v66
	v_div_fixup_f32 v60, v61, v60, 1.0
	v_fma_f32 v60, v52, v60, v36
	v_max_f32_e32 v60, 0xda24260, v60
	v_cmp_gt_f32_e32 vcc, s56, v60
	s_nop 1
	v_cndmask_b32_e64 v61, 0, 32, vcc
	v_ldexp_f32 v60, v60, v61
	v_log_f32_e32 v60, v60
	s_nop 0
	v_mul_f32_e32 v61, 0x3f317217, v60
	v_fma_f32 v61, v60, s57, -v61
	v_fmac_f32_e32 v61, 0x3377d1cf, v60
	v_fmac_f32_e32 v61, 0x3f317217, v60
	v_cmp_lt_f32_e64 s[0:1], |v60|, s8
	s_nop 1
	v_cndmask_b32_e64 v60, v60, v61, s[0:1]
	v_cndmask_b32_e32 v61, 0, v201, vcc
	v_sub_f32_e32 v64, v60, v61
	v_div_scale_f32 v60, s[0:1], v59, v59, 1.0
	v_rcp_f32_e32 v61, v60
	s_nop 0
	v_fma_f32 v65, -v60, v61, 1.0
	v_fmac_f32_e32 v61, v65, v61
	v_div_scale_f32 v65, vcc, 1.0, v59, 1.0
	v_mul_f32_e32 v66, v65, v61
	v_fma_f32 v67, -v60, v66, v65
	v_fmac_f32_e32 v66, v67, v61
	v_fma_f32 v60, -v60, v66, v65
	v_div_fmas_f32 v60, v60, v61, v66
	v_div_fixup_f32 v59, v60, v59, 1.0
	v_fma_f32 v59, v51, v59, v37
	v_max_f32_e32 v59, 0xda24260, v59
	v_cmp_gt_f32_e32 vcc, s56, v59
	s_nop 1
	v_cndmask_b32_e64 v60, 0, 32, vcc
	v_ldexp_f32 v59, v59, v60
	v_log_f32_e32 v59, v59
	s_nop 0
	v_mul_f32_e32 v60, 0x3f317217, v59
	v_fma_f32 v60, v59, s57, -v60
	v_fmac_f32_e32 v60, 0x3377d1cf, v59
	v_fmac_f32_e32 v60, 0x3f317217, v59
	v_cmp_lt_f32_e64 s[0:1], |v59|, s8
	s_nop 1
	v_cndmask_b32_e64 v59, v59, v60, s[0:1]
	v_cndmask_b32_e32 v60, 0, v201, vcc
	v_sub_f32_e32 v65, v59, v60
	ds_write_b128 v47, v[42:45] offset:8448
	ds_write_b128 v47, v[62:65] offset:8464
	v_or_b32_e32 v42, 32, v46
	v_ashrrev_i32_e32 v43, 31, v42
	v_lshlrev_b64 v[42:43], 12, v[42:43]
	v_lshl_add_u64 v[42:43], s[22:23], 0, v[42:43]
	v_lshl_add_u64 v[42:43], v[42:43], 0, s[58:59]
	v_lshl_add_u64 v[42:43], v[42:43], 0, v[48:49]
	s_waitcnt vmcnt(1)
	v_mov_b64_e32 v[42:43], v[102:103]
	v_mov_b64_e32 v[44:45], v[104:105]
	v_lshlrev_b32_e32 v59, 16, v42
	v_and_b32_e32 v60, 0xffff0000, v42
	v_mul_f32_e32 v42, 0xbfb8aa3b, v59
	v_exp_f32_e32 v42, v42
	v_lshlrev_b32_e32 v61, 16, v43
	v_and_b32_e32 v62, 0xffff0000, v43
	v_lshlrev_b32_e32 v63, 16, v44
	v_add_f32_e32 v42, 1.0, v42
	v_div_scale_f32 v43, s[0:1], v42, v42, 1.0
	v_and_b32_e32 v64, 0xffff0000, v44
	v_rcp_f32_e32 v44, v43
	v_lshlrev_b32_e32 v65, 16, v45
	v_and_b32_e32 v66, 0xffff0000, v45
	v_fma_f32 v45, -v43, v44, 1.0
	v_fmac_f32_e32 v44, v45, v44
	v_div_scale_f32 v45, vcc, 1.0, v42, 1.0
	v_mul_f32_e32 v59, v45, v44
	v_fma_f32 v67, -v43, v59, v45
	v_fmac_f32_e32 v59, v67, v44
	v_fma_f32 v43, -v43, v59, v45
	v_div_fmas_f32 v43, v43, v44, v59
	v_div_fixup_f32 v42, v43, v42, 1.0
	v_fma_f32 v42, v58, v42, v38
	v_max_f32_e32 v42, 0xda24260, v42
	v_cmp_gt_f32_e32 vcc, s56, v42
	s_nop 1
	v_cndmask_b32_e64 v43, 0, 32, vcc
	v_ldexp_f32 v42, v42, v43
	v_log_f32_e32 v42, v42
	s_nop 0
	v_mul_f32_e32 v43, 0x3f317217, v42
	v_fma_f32 v43, v42, s57, -v43
	v_fmac_f32_e32 v43, 0x3377d1cf, v42
	v_fmac_f32_e32 v43, 0x3f317217, v42
	v_cmp_lt_f32_e64 s[0:1], |v42|, s8
	s_nop 1
	v_cndmask_b32_e64 v42, v42, v43, s[0:1]
	v_cndmask_b32_e32 v43, 0, v201, vcc
	v_sub_f32_e32 v42, v42, v43
	v_mul_f32_e32 v43, 0xbfb8aa3b, v60
	v_exp_f32_e32 v43, v43
	s_nop 0
	v_add_f32_e32 v43, 1.0, v43
	v_div_scale_f32 v44, s[0:1], v43, v43, 1.0
	v_rcp_f32_e32 v45, v44
	s_nop 0
	v_fma_f32 v59, -v44, v45, 1.0
	v_fmac_f32_e32 v45, v59, v45
	v_div_scale_f32 v59, vcc, 1.0, v43, 1.0
	v_mul_f32_e32 v60, v59, v45
	v_fma_f32 v67, -v44, v60, v59
	v_fmac_f32_e32 v60, v67, v45
	v_fma_f32 v44, -v44, v60, v59
	v_div_fmas_f32 v44, v44, v45, v60
	v_div_fixup_f32 v43, v44, v43, 1.0
	v_fma_f32 v43, v57, v43, v39
	v_max_f32_e32 v43, 0xda24260, v43
	v_cmp_gt_f32_e32 vcc, s56, v43
	s_nop 1
	v_cndmask_b32_e64 v44, 0, 32, vcc
	v_ldexp_f32 v43, v43, v44
	v_log_f32_e32 v43, v43
	s_nop 0
	v_mul_f32_e32 v44, 0x3f317217, v43
	v_fma_f32 v44, v43, s57, -v44
	v_fmac_f32_e32 v44, 0x3377d1cf, v43
	v_fmac_f32_e32 v44, 0x3f317217, v43
	v_cmp_lt_f32_e64 s[0:1], |v43|, s8
	s_nop 1
	v_cndmask_b32_e64 v43, v43, v44, s[0:1]
	v_cndmask_b32_e32 v44, 0, v201, vcc
	v_sub_f32_e32 v43, v43, v44
	v_mul_f32_e32 v44, 0xbfb8aa3b, v61
	v_exp_f32_e32 v44, v44
	s_nop 0
	v_add_f32_e32 v44, 1.0, v44
	v_div_scale_f32 v45, s[0:1], v44, v44, 1.0
	v_rcp_f32_e32 v59, v45
	s_nop 0
	v_fma_f32 v60, -v45, v59, 1.0
	v_fmac_f32_e32 v59, v60, v59
	v_div_scale_f32 v60, vcc, 1.0, v44, 1.0
	v_mul_f32_e32 v61, v60, v59
	v_fma_f32 v67, -v45, v61, v60
	v_fmac_f32_e32 v61, v67, v59
	v_fma_f32 v45, -v45, v61, v60
	v_div_fmas_f32 v45, v45, v59, v61
	v_div_fixup_f32 v44, v45, v44, 1.0
	v_fma_f32 v44, v56, v44, v40
	v_max_f32_e32 v44, 0xda24260, v44
	v_cmp_gt_f32_e32 vcc, s56, v44
	s_nop 1
	v_cndmask_b32_e64 v45, 0, 32, vcc
	v_ldexp_f32 v44, v44, v45
	v_log_f32_e32 v44, v44
	s_nop 0
	v_mul_f32_e32 v45, 0x3f317217, v44
; __device__ __forceinline__ float sigmoidf_(float x) { return 1.0f / (1.0f + __expf(-x)); }
; __device__ __forceinline__ void hg_bcum(const Params& p, int l, const u16* Uhg, int t0, int h, float* bc, float* lbs,
;                                         float* tots) {
;     ...
;   for (int k = 0; k < 4; ++k) {
;     const int s = (tid >> 4) + 16 * k, d0 = (tid & 15) * 8;
;     float z[8];
;     unpack8(*(const uint4*)(Uhg + (size_t)(t0 + s) * 2048 + 512 + h * 128 + d0), z);
;     float lf[8];
; #pragma unroll
;     for (int j = 0; j < 8; ++j) {
;       const float lbv = lbs[d0 + j];
;       const float f = lbv + (1.0f - lbv) * sigmoidf_(z[j]);
;       lf[j] = __logf(fmaxf(f, 1e-30f));
;     }
;     *(float4*)(bc + s * BCS + d0) = make_float4(lf[0], lf[1], lf[2], lf[3]);
;     *(float4*)(bc + s * BCS + d0 + 4) = make_float4(lf[4], lf[5], lf[6], lf[7]);
	v_fma_f32 v45, v44, s57, -v45
	v_fmac_f32_e32 v45, 0x3377d1cf, v44
	v_fmac_f32_e32 v45, 0x3f317217, v44
	v_cmp_lt_f32_e64 s[0:1], |v44|, s8
	s_nop 1
	v_cndmask_b32_e64 v44, v44, v45, s[0:1]
	v_cndmask_b32_e32 v45, 0, v201, vcc
	v_sub_f32_e32 v44, v44, v45
	v_mul_f32_e32 v45, 0xbfb8aa3b, v62
	v_exp_f32_e32 v45, v45
	s_nop 0
	v_add_f32_e32 v45, 1.0, v45
	v_div_scale_f32 v59, s[0:1], v45, v45, 1.0
	v_rcp_f32_e32 v60, v59
	s_nop 0
	v_fma_f32 v61, -v59, v60, 1.0
	v_fmac_f32_e32 v60, v61, v60
	v_div_scale_f32 v61, vcc, 1.0, v45, 1.0
	v_mul_f32_e32 v62, v61, v60
	v_fma_f32 v67, -v59, v62, v61
	v_fmac_f32_e32 v62, v67, v60
	v_fma_f32 v59, -v59, v62, v61
	v_div_fmas_f32 v59, v59, v60, v62
	v_div_fixup_f32 v45, v59, v45, 1.0
	v_fma_f32 v45, v55, v45, v41
	v_max_f32_e32 v45, 0xda24260, v45
	v_cmp_gt_f32_e32 vcc, s56, v45
	s_nop 1
	v_cndmask_b32_e64 v59, 0, 32, vcc
	v_ldexp_f32 v45, v45, v59
	v_log_f32_e32 v45, v45
	s_nop 0
	v_mul_f32_e32 v59, 0x3f317217, v45
	v_fma_f32 v59, v45, s57, -v59
	v_fmac_f32_e32 v59, 0x3377d1cf, v45
	v_fmac_f32_e32 v59, 0x3f317217, v45
	v_cmp_lt_f32_e64 s[0:1], |v45|, s8
	s_nop 1
	v_cndmask_b32_e64 v45, v45, v59, s[0:1]
	v_cndmask_b32_e32 v59, 0, v201, vcc
	v_sub_f32_e32 v45, v45, v59
	v_mul_f32_e32 v59, 0xbfb8aa3b, v63
	v_exp_f32_e32 v59, v59
	s_nop 0
	v_add_f32_e32 v59, 1.0, v59
	v_div_scale_f32 v60, s[0:1], v59, v59, 1.0
	v_rcp_f32_e32 v61, v60
	s_nop 0
	v_fma_f32 v62, -v60, v61, 1.0
	v_fmac_f32_e32 v61, v62, v61
	v_div_scale_f32 v62, vcc, 1.0, v59, 1.0
	v_mul_f32_e32 v63, v62, v61
	v_fma_f32 v67, -v60, v63, v62
	v_fmac_f32_e32 v63, v67, v61
	v_fma_f32 v60, -v60, v63, v62
	v_div_fmas_f32 v60, v60, v61, v63
	v_div_fixup_f32 v59, v60, v59, 1.0
	v_fma_f32 v59, v54, v59, v34
	v_max_f32_e32 v59, 0xda24260, v59
	v_cmp_gt_f32_e32 vcc, s56, v59
	s_nop 1
	v_cndmask_b32_e64 v60, 0, 32, vcc
	v_ldexp_f32 v59, v59, v60
	v_log_f32_e32 v59, v59
	s_nop 0
	v_mul_f32_e32 v60, 0x3f317217, v59
	v_fma_f32 v60, v59, s57, -v60
	v_fmac_f32_e32 v60, 0x3377d1cf, v59
	v_fmac_f32_e32 v60, 0x3f317217, v59
	v_cmp_lt_f32_e64 s[0:1], |v59|, s8
	s_nop 1
	v_cndmask_b32_e64 v59, v59, v60, s[0:1]
	v_cndmask_b32_e32 v60, 0, v201, vcc
	v_sub_f32_e32 v60, v59, v60
	v_mul_f32_e32 v59, 0xbfb8aa3b, v64
	v_exp_f32_e32 v59, v59
	s_nop 0
	v_add_f32_e32 v59, 1.0, v59
	v_div_scale_f32 v61, s[0:1], v59, v59, 1.0
	v_rcp_f32_e32 v62, v61
	s_nop 0
	v_fma_f32 v63, -v61, v62, 1.0
	v_fmac_f32_e32 v62, v63, v62
	v_div_scale_f32 v63, vcc, 1.0, v59, 1.0
	v_mul_f32_e32 v64, v63, v62
	v_fma_f32 v67, -v61, v64, v63
	v_fmac_f32_e32 v64, v67, v62
	v_fma_f32 v61, -v61, v64, v63
	v_div_fmas_f32 v61, v61, v62, v64
	v_div_fixup_f32 v59, v61, v59, 1.0
	v_fma_f32 v59, v53, v59, v35
	v_max_f32_e32 v59, 0xda24260, v59
	v_cmp_gt_f32_e32 vcc, s56, v59
	s_nop 1
	v_cndmask_b32_e64 v61, 0, 32, vcc
	v_ldexp_f32 v59, v59, v61
	v_log_f32_e32 v59, v59
	s_nop 0
	v_mul_f32_e32 v61, 0x3f317217, v59
	v_fma_f32 v61, v59, s57, -v61
	v_fmac_f32_e32 v61, 0x3377d1cf, v59
	v_fmac_f32_e32 v61, 0x3f317217, v59
	v_cmp_lt_f32_e64 s[0:1], |v59|, s8
	s_nop 1
	v_cndmask_b32_e64 v59, v59, v61, s[0:1]
	v_cndmask_b32_e32 v61, 0, v201, vcc
	v_sub_f32_e32 v61, v59, v61
	v_mul_f32_e32 v59, 0xbfb8aa3b, v65
	v_exp_f32_e32 v59, v59
	s_nop 0
	v_add_f32_e32 v59, 1.0, v59
	v_div_scale_f32 v62, s[0:1], v59, v59, 1.0
	v_rcp_f32_e32 v63, v62
	s_nop 0
	v_fma_f32 v64, -v62, v63, 1.0
	v_fmac_f32_e32 v63, v64, v63
	v_div_scale_f32 v64, vcc, 1.0, v59, 1.0
	v_mul_f32_e32 v65, v64, v63
	v_fma_f32 v67, -v62, v65, v64
	v_fmac_f32_e32 v65, v67, v63
	v_fma_f32 v62, -v62, v65, v64
	v_div_fmas_f32 v62, v62, v63, v65
	v_div_fixup_f32 v59, v62, v59, 1.0
	v_fma_f32 v59, v52, v59, v36
	v_max_f32_e32 v59, 0xda24260, v59
	v_cmp_gt_f32_e32 vcc, s56, v59
	s_nop 1
	v_cndmask_b32_e64 v62, 0, 32, vcc
	v_ldexp_f32 v59, v59, v62
	v_log_f32_e32 v59, v59
	s_nop 0
	v_mul_f32_e32 v62, 0x3f317217, v59
	v_fma_f32 v62, v59, s57, -v62
	v_fmac_f32_e32 v62, 0x3377d1cf, v59
	v_fmac_f32_e32 v62, 0x3f317217, v59
	v_cmp_lt_f32_e64 s[0:1], |v59|, s8
	s_nop 1
	v_cndmask_b32_e64 v59, v59, v62, s[0:1]
	v_cndmask_b32_e32 v62, 0, v201, vcc
	v_sub_f32_e32 v62, v59, v62
	v_mul_f32_e32 v59, 0xbfb8aa3b, v66
	v_exp_f32_e32 v59, v59
	s_nop 0
	v_add_f32_e32 v59, 1.0, v59
	v_div_scale_f32 v63, s[0:1], v59, v59, 1.0
	v_rcp_f32_e32 v64, v63
	s_nop 0
	v_fma_f32 v65, -v63, v64, 1.0
	v_fmac_f32_e32 v64, v65, v64
	v_div_scale_f32 v65, vcc, 1.0, v59, 1.0
	v_mul_f32_e32 v66, v65, v64
	v_fma_f32 v67, -v63, v66, v65
	v_fmac_f32_e32 v66, v67, v64
	v_fma_f32 v63, -v63, v66, v65
	v_div_fmas_f32 v63, v63, v64, v66
	v_div_fixup_f32 v59, v63, v59, 1.0
	v_fma_f32 v59, v51, v59, v37
	v_max_f32_e32 v59, 0xda24260, v59
	v_cmp_gt_f32_e32 vcc, s56, v59
	s_nop 1
	v_cndmask_b32_e64 v63, 0, 32, vcc
	v_ldexp_f32 v59, v59, v63
	v_log_f32_e32 v59, v59
	s_nop 0
	v_mul_f32_e32 v63, 0x3f317217, v59
	v_fma_f32 v63, v59, s57, -v63
	v_fmac_f32_e32 v63, 0x3377d1cf, v59
	v_fmac_f32_e32 v63, 0x3f317217, v59
	v_cmp_lt_f32_e64 s[0:1], |v59|, s8
	s_nop 1
	v_cndmask_b32_e64 v59, v59, v63, s[0:1]
	v_cndmask_b32_e32 v63, 0, v201, vcc
	v_sub_f32_e32 v63, v59, v63
	ds_write_b128 v47, v[42:45] offset:16896
	ds_write_b128 v47, v[60:63] offset:16912
	v_or_b32_e32 v42, 48, v46
	v_ashrrev_i32_e32 v43, 31, v42
	v_lshlrev_b64 v[42:43], 12, v[42:43]
	v_lshl_add_u64 v[42:43], s[22:23], 0, v[42:43]
	v_lshl_add_u64 v[42:43], v[42:43], 0, s[58:59]
	v_lshl_add_u64 v[42:43], v[42:43], 0, v[48:49]
	s_waitcnt vmcnt(0)
; __device__ __forceinline__ float sigmoidf_(float x) { return 1.0f / (1.0f + __expf(-x)); }
; __device__ __forceinline__ void hg_bcum(const Params& p, int l, const u16* Uhg, int t0, int h, float* bc, float* lbs,
;                                         float* tots) {
;     ...
;   for (int k = 0; k < 4; ++k) {
;     const int s = (tid >> 4) + 16 * k, d0 = (tid & 15) * 8;
;     float z[8];
;     unpack8(*(const uint4*)(Uhg + (size_t)(t0 + s) * 2048 + 512 + h * 128 + d0), z);
;     float lf[8];
; #pragma unroll
;     for (int j = 0; j < 8; ++j) {
;       const float lbv = lbs[d0 + j];
;       const float f = lbv + (1.0f - lbv) * sigmoidf_(z[j]);
;       lf[j] = __logf(fmaxf(f, 1e-30f));
;     }
;     *(float4*)(bc + s * BCS + d0) = make_float4(lf[0], lf[1], lf[2], lf[3]);
;     *(float4*)(bc + s * BCS + d0 + 4) = make_float4(lf[4], lf[5], lf[6], lf[7]);
	v_mov_b64_e32 v[42:43], v[106:107]
	v_mov_b64_e32 v[44:45], v[108:109]
	v_lshlrev_b32_e32 v46, 16, v42
	v_and_b32_e32 v48, 0xffff0000, v42
	v_lshlrev_b32_e32 v49, 16, v43
	v_and_b32_e32 v59, 0xffff0000, v43
	v_lshlrev_b32_e32 v43, 16, v45
	v_and_b32_e32 v42, 0xffff0000, v45
	v_mul_f32_e32 v45, 0xbfb8aa3b, v46
	v_exp_f32_e32 v45, v45
	v_lshlrev_b32_e32 v60, 16, v44
	v_and_b32_e32 v44, 0xffff0000, v44
	v_mul_f32_e32 v44, 0xbfb8aa3b, v44
	v_add_f32_e32 v45, 1.0, v45
	v_div_scale_f32 v46, s[0:1], v45, v45, 1.0
	v_rcp_f32_e32 v61, v46
	v_exp_f32_e32 v44, v44
	v_mul_f32_e32 v43, 0xbfb8aa3b, v43
	v_exp_f32_e32 v43, v43
	v_fma_f32 v62, -v46, v61, 1.0
	v_fmac_f32_e32 v61, v62, v61
	v_div_scale_f32 v62, vcc, 1.0, v45, 1.0
	v_mul_f32_e32 v63, v62, v61
	v_fma_f32 v64, -v46, v63, v62
	v_fmac_f32_e32 v63, v64, v61
	v_fma_f32 v46, -v46, v63, v62
	v_div_fmas_f32 v46, v46, v61, v63
	v_div_fixup_f32 v45, v46, v45, 1.0
	v_fma_f32 v38, v58, v45, v38
	v_max_f32_e32 v38, 0xda24260, v38
	v_cmp_gt_f32_e32 vcc, s56, v38
	v_add_f32_e32 v44, 1.0, v44
	v_add_f32_e32 v43, 1.0, v43
	v_cndmask_b32_e64 v45, 0, 32, vcc
	v_ldexp_f32 v38, v38, v45
	v_log_f32_e32 v38, v38
	v_mul_f32_e32 v42, 0xbfb8aa3b, v42
	v_exp_f32_e32 v42, v42
	v_mul_f32_e32 v45, 0x3f317217, v38
	v_fma_f32 v45, v38, s57, -v45
	v_fmac_f32_e32 v45, 0x3377d1cf, v38
	v_fmac_f32_e32 v45, 0x3f317217, v38
	v_cmp_lt_f32_e64 s[0:1], |v38|, s8
	v_add_f32_e32 v42, 1.0, v42
	s_nop 0
	v_cndmask_b32_e64 v38, v38, v45, s[0:1]
	v_cndmask_b32_e32 v45, 0, v201, vcc
	v_sub_f32_e32 v38, v38, v45
	v_mul_f32_e32 v45, 0xbfb8aa3b, v48
	v_exp_f32_e32 v45, v45
	s_nop 0
	v_add_f32_e32 v45, 1.0, v45
	v_div_scale_f32 v46, s[0:1], v45, v45, 1.0
	v_rcp_f32_e32 v48, v46
	s_nop 0
	v_fma_f32 v58, -v46, v48, 1.0
	v_fmac_f32_e32 v48, v58, v48
	v_div_scale_f32 v58, vcc, 1.0, v45, 1.0
	v_mul_f32_e32 v61, v58, v48
	v_fma_f32 v62, -v46, v61, v58
	v_fmac_f32_e32 v61, v62, v48
	v_fma_f32 v46, -v46, v61, v58
	v_div_fmas_f32 v46, v46, v48, v61
	v_div_fixup_f32 v45, v46, v45, 1.0
	v_fma_f32 v39, v57, v45, v39
	v_max_f32_e32 v39, 0xda24260, v39
	v_cmp_gt_f32_e32 vcc, s56, v39
	s_nop 1
	v_cndmask_b32_e64 v45, 0, 32, vcc
	v_ldexp_f32 v39, v39, v45
	v_log_f32_e32 v39, v39
	s_nop 0
	v_mul_f32_e32 v45, 0x3f317217, v39
	v_fma_f32 v45, v39, s57, -v45
	v_fmac_f32_e32 v45, 0x3377d1cf, v39
	v_fmac_f32_e32 v45, 0x3f317217, v39
	v_cmp_lt_f32_e64 s[0:1], |v39|, s8
	s_nop 1
	v_cndmask_b32_e64 v39, v39, v45, s[0:1]
	v_cndmask_b32_e32 v45, 0, v201, vcc
	v_sub_f32_e32 v39, v39, v45
	v_mul_f32_e32 v45, 0xbfb8aa3b, v49
	v_exp_f32_e32 v45, v45
	s_nop 0
	v_add_f32_e32 v45, 1.0, v45
	v_div_scale_f32 v46, s[0:1], v45, v45, 1.0
	v_rcp_f32_e32 v48, v46
	s_nop 0
	v_fma_f32 v49, -v46, v48, 1.0
	v_fmac_f32_e32 v48, v49, v48
	v_div_scale_f32 v49, vcc, 1.0, v45, 1.0
	v_mul_f32_e32 v57, v49, v48
	v_fma_f32 v58, -v46, v57, v49
	v_fmac_f32_e32 v57, v58, v48
	v_fma_f32 v46, -v46, v57, v49
	v_div_fmas_f32 v46, v46, v48, v57
	v_div_fixup_f32 v45, v46, v45, 1.0
	v_fma_f32 v40, v56, v45, v40
	v_max_f32_e32 v40, 0xda24260, v40
	v_cmp_gt_f32_e32 vcc, s56, v40
	s_nop 1
	v_cndmask_b32_e64 v45, 0, 32, vcc
	v_ldexp_f32 v40, v40, v45
	v_log_f32_e32 v40, v40
	s_nop 0
	v_mul_f32_e32 v45, 0x3f317217, v40
	v_fma_f32 v45, v40, s57, -v45
	v_fmac_f32_e32 v45, 0x3377d1cf, v40
	v_fmac_f32_e32 v45, 0x3f317217, v40
	v_cmp_lt_f32_e64 s[0:1], |v40|, s8
	s_nop 1
	v_cndmask_b32_e64 v40, v40, v45, s[0:1]
	v_cndmask_b32_e32 v45, 0, v201, vcc
	v_sub_f32_e32 v40, v40, v45
	v_mul_f32_e32 v45, 0xbfb8aa3b, v59
	v_exp_f32_e32 v45, v45
	s_nop 0
	v_add_f32_e32 v45, 1.0, v45
	v_div_scale_f32 v46, s[0:1], v45, v45, 1.0
	v_rcp_f32_e32 v48, v46
	s_nop 0
	v_fma_f32 v49, -v46, v48, 1.0
	v_fmac_f32_e32 v48, v49, v48
	v_div_scale_f32 v49, vcc, 1.0, v45, 1.0
	v_mul_f32_e32 v56, v49, v48
	v_fma_f32 v57, -v46, v56, v49
	v_fmac_f32_e32 v56, v57, v48
	v_fma_f32 v46, -v46, v56, v49
	v_div_fmas_f32 v46, v46, v48, v56
	v_div_fixup_f32 v45, v46, v45, 1.0
	v_fmac_f32_e32 v41, v55, v45
	v_max_f32_e32 v41, 0xda24260, v41
	v_cmp_gt_f32_e32 vcc, s56, v41
	s_nop 1
	v_cndmask_b32_e64 v45, 0, 32, vcc
	v_ldexp_f32 v41, v41, v45
	v_log_f32_e32 v41, v41
	s_nop 0
	v_mul_f32_e32 v45, 0x3f317217, v41
	v_fma_f32 v45, v41, s57, -v45
	v_fmac_f32_e32 v45, 0x3377d1cf, v41
	v_fmac_f32_e32 v45, 0x3f317217, v41
	v_cmp_lt_f32_e64 s[0:1], |v41|, s8
	s_nop 1
	v_cndmask_b32_e64 v41, v41, v45, s[0:1]
	v_cndmask_b32_e32 v45, 0, v201, vcc
	v_sub_f32_e32 v41, v41, v45
	v_mul_f32_e32 v45, 0xbfb8aa3b, v60
	v_exp_f32_e32 v45, v45
	s_nop 0
	v_add_f32_e32 v45, 1.0, v45
	v_div_scale_f32 v46, s[0:1], v45, v45, 1.0
	v_rcp_f32_e32 v48, v46
	s_nop 0
	v_fma_f32 v49, -v46, v48, 1.0
	v_fmac_f32_e32 v48, v49, v48
	v_div_scale_f32 v49, vcc, 1.0, v45, 1.0
	v_mul_f32_e32 v55, v49, v48
	v_fma_f32 v56, -v46, v55, v49
	v_fmac_f32_e32 v55, v56, v48
	v_fma_f32 v46, -v46, v55, v49
	v_div_fmas_f32 v46, v46, v48, v55
	v_div_fixup_f32 v45, v46, v45, 1.0
	v_fma_f32 v34, v54, v45, v34
	v_max_f32_e32 v34, 0xda24260, v34
	v_cmp_gt_f32_e32 vcc, s56, v34
	s_nop 1
	v_cndmask_b32_e64 v45, 0, 32, vcc
	v_ldexp_f32 v34, v34, v45
	v_log_f32_e32 v34, v34
	s_nop 0
	v_mul_f32_e32 v45, 0x3f317217, v34
	v_fma_f32 v45, v34, s57, -v45
	v_fmac_f32_e32 v45, 0x3377d1cf, v34
	v_fmac_f32_e32 v45, 0x3f317217, v34
	v_cmp_lt_f32_e64 s[0:1], |v34|, s8
	s_nop 1
	v_cndmask_b32_e64 v34, v34, v45, s[0:1]
	v_cndmask_b32_e32 v45, 0, v201, vcc
	v_sub_f32_e32 v34, v34, v45
	v_div_scale_f32 v45, s[0:1], v44, v44, 1.0
	v_rcp_f32_e32 v46, v45
	s_nop 0
	v_fma_f32 v48, -v45, v46, 1.0
	v_fmac_f32_e32 v46, v48, v46
	v_div_scale_f32 v48, vcc, 1.0, v44, 1.0
	v_mul_f32_e32 v49, v48, v46
	v_fma_f32 v54, -v45, v49, v48
; __device__ __forceinline__ float sigmoidf_(float x) { return 1.0f / (1.0f + __expf(-x)); }
; __device__ __forceinline__ void hg_bcum(const Params& p, int l, const u16* Uhg, int t0, int h, float* bc, float* lbs,
;                                         float* tots) {
;     ...
;     float lf[8];
; #pragma unroll
;     for (int j = 0; j < 8; ++j) {
;       const float lbv = lbs[d0 + j];
;       const float f = lbv + (1.0f - lbv) * sigmoidf_(z[j]);
;       lf[j] = __logf(fmaxf(f, 1e-30f));
;     }
;     *(float4*)(bc + s * BCS + d0) = make_float4(lf[0], lf[1], lf[2], lf[3]);
;     *(float4*)(bc + s * BCS + d0 + 4) = make_float4(lf[4], lf[5], lf[6], lf[7]);
;   }
;   __syncthreads();
;   {
;     const int d = tid & 127, hf = tid >> 7;
;     float r[32];
;     float run = 0.f;
; #pragma unroll
;     for (int s = 0; s < 32; ++s) { run += bc[(hf * 32 + s) * BCS + d]; r[s] = run; }
;     if (hf == 0) tots[d] = run;
;     __syncthreads();
	v_fmac_f32_e32 v49, v54, v46
	v_fma_f32 v45, -v45, v49, v48
	v_div_fmas_f32 v45, v45, v46, v49
	v_div_fixup_f32 v44, v45, v44, 1.0
	v_fma_f32 v35, v53, v44, v35
	v_max_f32_e32 v35, 0xda24260, v35
	v_cmp_gt_f32_e32 vcc, s56, v35
	s_nop 1
	v_cndmask_b32_e64 v44, 0, 32, vcc
	v_ldexp_f32 v35, v35, v44
	v_log_f32_e32 v35, v35
	s_nop 0
	v_mul_f32_e32 v44, 0x3f317217, v35
	v_fma_f32 v44, v35, s57, -v44
	v_fmac_f32_e32 v44, 0x3377d1cf, v35
	v_fmac_f32_e32 v44, 0x3f317217, v35
	v_cmp_lt_f32_e64 s[0:1], |v35|, s8
	s_nop 1
	v_cndmask_b32_e64 v35, v35, v44, s[0:1]
	v_cndmask_b32_e32 v44, 0, v201, vcc
	v_sub_f32_e32 v35, v35, v44
	v_div_scale_f32 v44, s[0:1], v43, v43, 1.0
	v_rcp_f32_e32 v45, v44
	s_nop 0
	v_fma_f32 v46, -v44, v45, 1.0
	v_fmac_f32_e32 v45, v46, v45
	v_div_scale_f32 v46, vcc, 1.0, v43, 1.0
	v_mul_f32_e32 v48, v46, v45
	v_fma_f32 v49, -v44, v48, v46
	v_fmac_f32_e32 v48, v49, v45
	v_fma_f32 v44, -v44, v48, v46
	v_div_fmas_f32 v44, v44, v45, v48
	v_div_fixup_f32 v43, v44, v43, 1.0
	v_fma_f32 v36, v52, v43, v36
	v_max_f32_e32 v36, 0xda24260, v36
	v_cmp_gt_f32_e32 vcc, s56, v36
	s_nop 1
	v_cndmask_b32_e64 v43, 0, 32, vcc
	v_ldexp_f32 v36, v36, v43
	v_log_f32_e32 v36, v36
	s_nop 0
	v_mul_f32_e32 v43, 0x3f317217, v36
	v_fma_f32 v43, v36, s57, -v43
	v_fmac_f32_e32 v43, 0x3377d1cf, v36
	v_fmac_f32_e32 v43, 0x3f317217, v36
	v_cmp_lt_f32_e64 s[0:1], |v36|, s8
	s_nop 1
	v_cndmask_b32_e64 v36, v36, v43, s[0:1]
	v_cndmask_b32_e32 v43, 0, v201, vcc
	v_sub_f32_e32 v36, v36, v43
	v_div_scale_f32 v43, s[0:1], v42, v42, 1.0
	v_rcp_f32_e32 v44, v43
	s_nop 0
	v_fma_f32 v45, -v43, v44, 1.0
	v_fmac_f32_e32 v44, v45, v44
	v_div_scale_f32 v45, vcc, 1.0, v42, 1.0
	v_mul_f32_e32 v46, v45, v44
	v_fma_f32 v48, -v43, v46, v45
	v_fmac_f32_e32 v46, v48, v44
	v_fma_f32 v43, -v43, v46, v45
	v_div_fmas_f32 v43, v43, v44, v46
	v_div_fixup_f32 v42, v43, v42, 1.0
	v_fmac_f32_e32 v37, v51, v42
	v_max_f32_e32 v37, 0xda24260, v37
	v_cmp_gt_f32_e32 vcc, s56, v37
	s_nop 1
	v_cndmask_b32_e64 v42, 0, 32, vcc
	v_ldexp_f32 v37, v37, v42
	v_log_f32_e32 v37, v37
	s_nop 0
	v_mul_f32_e32 v42, 0x3f317217, v37
	v_fma_f32 v42, v37, s57, -v42
	v_fmac_f32_e32 v42, 0x3377d1cf, v37
	v_fmac_f32_e32 v42, 0x3f317217, v37
	v_cmp_lt_f32_e64 s[0:1], |v37|, s8
	s_nop 1
	v_cndmask_b32_e64 v37, v37, v42, s[0:1]
	v_cndmask_b32_e32 v42, 0, v201, vcc
	v_sub_f32_e32 v37, v37, v42
	ds_write_b128 v47, v[38:41] offset:25344
	ds_write_b128 v47, v[34:37] offset:25360
	v_lshrrev_b32_e32 v34, 2, v50
	v_and_b32_e32 v36, 0x7f, v50
	v_and_b32_e32 v34, 32, v34
	v_mul_u32_u24_e32 v34, 0x210, v34
	v_lshlrev_b32_e32 v35, 2, v36
	v_add3_u32 v34, s69, v34, v35
	s_waitcnt lgkmcnt(0)
	s_barrier
	ds_read2_b32 v[38:39], v34 offset1:132
	v_add_u32_e32 v35, 0x400, v34
	ds_read2_b32 v[40:41], v35 offset0:8 offset1:140
	v_add_u32_e32 v44, 0xc00, v34
	ds_read2_b32 v[46:47], v44 offset0:24 offset1:156
	s_waitcnt lgkmcnt(2)
	v_add_f32_e32 v37, 0, v38
	v_add_f32_e32 v38, v37, v39
	s_waitcnt lgkmcnt(1)
	v_add_f32_e32 v39, v38, v40
	v_add_f32_e32 v40, v39, v41
	v_add_u32_e32 v41, 0x800, v34
	ds_read2_b32 v[42:43], v41 offset0:16 offset1:148
	v_add_u32_e32 v45, 0x1000, v34
	ds_read2_b32 v[48:49], v45 offset0:32 offset1:164
	v_add_u32_e32 v50, 0x1400, v34
	ds_read2_b32 v[52:53], v50 offset0:40 offset1:172
	s_waitcnt lgkmcnt(2)
	v_add_f32_e32 v42, v40, v42
	v_add_f32_e32 v43, v42, v43
	v_add_f32_e32 v46, v43, v46
	v_add_f32_e32 v47, v46, v47
	s_waitcnt lgkmcnt(1)
	v_add_f32_e32 v48, v47, v48
	v_add_f32_e32 v49, v48, v49
	s_waitcnt lgkmcnt(0)
	v_add_f32_e32 v51, v49, v52
	v_add_f32_e32 v52, v51, v53
	v_add_u32_e32 v53, 0x1800, v34
	ds_read2_b32 v[56:57], v53 offset0:48 offset1:180
	v_add_u32_e32 v54, 0x1c00, v34
	ds_read2_b32 v[58:59], v54 offset0:56 offset1:188
	v_add_u32_e32 v62, 0x2400, v34
	ds_read2_b32 v[64:65], v62 offset0:72 offset1:204
	s_waitcnt lgkmcnt(2)
	v_add_f32_e32 v55, v52, v56
	v_add_f32_e32 v56, v55, v57
	s_waitcnt lgkmcnt(1)
	v_add_f32_e32 v57, v56, v58
	v_add_f32_e32 v58, v57, v59
	v_add_u32_e32 v59, 0x2000, v34
	ds_read2_b32 v[60:61], v59 offset0:64 offset1:196
	v_add_u32_e32 v63, 0x2800, v34
	ds_read2_b32 v[66:67], v63 offset0:80 offset1:212
	v_add_u32_e32 v68, 0x2c00, v34
	ds_read2_b32 v[70:71], v68 offset0:88 offset1:220
	s_waitcnt lgkmcnt(2)
	v_add_f32_e32 v60, v58, v60
	v_add_f32_e32 v61, v60, v61
	v_add_f32_e32 v64, v61, v64
	v_add_f32_e32 v65, v64, v65
	s_waitcnt lgkmcnt(1)
	v_add_f32_e32 v66, v65, v66
	v_add_f32_e32 v67, v66, v67
	s_waitcnt lgkmcnt(0)
	v_add_f32_e32 v69, v67, v70
	v_add_f32_e32 v70, v69, v71
	v_add_u32_e32 v71, 0x3000, v34
	ds_read2_b32 v[74:75], v71 offset0:96 offset1:228
	v_add_u32_e32 v72, 0x3400, v34
	ds_read2_b32 v[76:77], v72 offset0:104 offset1:236
	v_add_u32_e32 v80, 0x3c00, v34
	ds_read2_b32 v[82:83], v80 offset0:120 offset1:252
	s_waitcnt lgkmcnt(2)
	v_add_f32_e32 v73, v70, v74
	v_add_f32_e32 v74, v73, v75
	s_waitcnt lgkmcnt(1)
	v_add_f32_e32 v75, v74, v76
	v_add_f32_e32 v76, v75, v77
	v_add_u32_e32 v77, 0x3800, v34
	ds_read2_b32 v[78:79], v77 offset0:112 offset1:244
	v_lshl_add_u32 v84, v36, 2, s71
	s_waitcnt lgkmcnt(0)
	v_add_f32_e32 v78, v76, v78
	v_add_f32_e32 v79, v78, v79
	v_add_f32_e32 v81, v79, v82
	v_add_f32_e32 v82, v81, v83
	s_and_saveexec_b64 s[0:1], s[48:49]
	ds_write_b32 v84, v82
	s_or_b64 exec, exec, s[0:1]
	v_mov_b32_e32 v36, 0
	v_mov_b32_e32 v83, 0
	s_waitcnt lgkmcnt(0)
	s_barrier
; __device__ __forceinline__ void hg_bcum(const Params& p, int l, const u16* Uhg, int t0, int h, float* bc, float* lbs,
;                                         float* tots) {
;     ...
;     const float add = hf ? tots[d] : 0.f;
; #pragma unroll
;     for (int s = 0; s < 32; ++s) bc[(hf * 32 + s) * BCS + d] = r[s] + add;
;   }
;   __syncthreads();
; __device__ __forceinline__ void phase_hg_out(const Params& p, int l, char* smem) {
;     ...
;       const int d = tid & 127;
;       for (int idx = tid; idx < 64 * 128; idx += 256) {
;         const int s = idx >> 7;
;         VTs[d * 72 + s] = Uhg[(size_t)(t0 + s) * 2048 + 1024 + h * 128 + d];
;       }
	s_and_saveexec_b64 s[0:1], s[46:47]
	ds_read_b32 v83, v84
	s_or_b64 exec, exec, s[0:1]
	s_waitcnt lgkmcnt(0)
	v_add_f32_e32 v37, v37, v83
	v_add_f32_e32 v38, v38, v83
	ds_write2_b32 v34, v37, v38 offset1:132
	v_add_f32_e32 v34, v39, v83
	v_add_f32_e32 v37, v40, v83
	ds_write2_b32 v35, v34, v37 offset0:8 offset1:140
	v_add_f32_e32 v34, v42, v83
	v_add_f32_e32 v35, v43, v83
	ds_write2_b32 v41, v34, v35 offset0:16 offset1:148
	v_add_f32_e32 v34, v46, v83
	v_add_f32_e32 v35, v47, v83
	ds_write2_b32 v44, v34, v35 offset0:24 offset1:156
	v_add_f32_e32 v34, v48, v83
	v_add_f32_e32 v35, v49, v83
	ds_write2_b32 v45, v34, v35 offset0:32 offset1:164
	v_add_f32_e32 v34, v51, v83
	v_add_f32_e32 v35, v52, v83
	ds_write2_b32 v50, v34, v35 offset0:40 offset1:172
	v_add_f32_e32 v34, v55, v83
	v_add_f32_e32 v35, v56, v83
	ds_write2_b32 v53, v34, v35 offset0:48 offset1:180
	v_add_f32_e32 v34, v57, v83
	v_add_f32_e32 v35, v58, v83
	ds_write2_b32 v54, v34, v35 offset0:56 offset1:188
	v_add_f32_e32 v34, v60, v83
	v_add_f32_e32 v35, v61, v83
	ds_write2_b32 v59, v34, v35 offset0:64 offset1:196
	v_add_f32_e32 v34, v64, v83
	v_add_f32_e32 v35, v65, v83
	ds_write2_b32 v62, v34, v35 offset0:72 offset1:204
	v_add_f32_e32 v34, v66, v83
	v_add_f32_e32 v35, v67, v83
	ds_write2_b32 v63, v34, v35 offset0:80 offset1:212
	v_add_f32_e32 v34, v69, v83
	v_add_f32_e32 v35, v70, v83
	ds_write2_b32 v68, v34, v35 offset0:88 offset1:220
	v_add_f32_e32 v34, v73, v83
	v_add_f32_e32 v35, v74, v83
	ds_write2_b32 v71, v34, v35 offset0:96 offset1:228
	v_add_f32_e32 v34, v75, v83
	v_add_f32_e32 v35, v76, v83
	s_lshl_b32 s0, s20, 7
	ds_write2_b32 v72, v34, v35 offset0:104 offset1:236
	v_add_f32_e32 v34, v78, v83
	v_add_f32_e32 v35, v79, v83
	v_or_b32_e32 v38, s13, v3
	v_or_b32_e32 v40, s13, v2
	v_or_b32_e32 v42, s13, v5
	v_or_b32_e32 v44, s13, v4
	ds_write2_b32 v77, v34, v35 offset0:112 offset1:244
	v_add_f32_e32 v34, v81, v83
	v_add_f32_e32 v35, v82, v83
	s_lshl_b32 s58, s0, 1
	v_ashrrev_i32_e32 v45, 31, v44
	v_ashrrev_i32_e32 v43, 31, v42
	v_ashrrev_i32_e32 v41, 31, v40
	v_ashrrev_i32_e32 v39, 31, v38
	ds_write2_b32 v80, v34, v35 offset0:120 offset1:252
	v_lshl_add_u64 v[34:35], v[136:137], 0, s[58:59]
	v_lshlrev_b64 v[38:39], 12, v[38:39]
	v_lshlrev_b64 v[40:41], 12, v[40:41]
	v_lshlrev_b64 v[42:43], 12, v[42:43]
	v_lshlrev_b64 v[44:45], 12, v[44:45]
	v_lshl_add_u64 v[44:45], v[34:35], 0, v[44:45]
	v_lshl_add_u64 v[42:43], v[34:35], 0, v[42:43]
	v_lshl_add_u64 v[40:41], v[34:35], 0, v[40:41]
	v_lshl_add_u64 v[38:39], v[34:35], 0, v[38:39]
	s_waitcnt lgkmcnt(0)
	s_barrier
	global_load_ushort v98, v[44:45], off offset:2048
	s_nop 0
	global_load_ushort v99, v[42:43], off offset:2048
	s_nop 0
	global_load_ushort v100, v[40:41], off offset:2048
	s_nop 0
	global_load_ushort v101, v[38:39], off offset:2048
	v_or_b32_e32 v44, s13, v8
	v_ashrrev_i32_e32 v45, 31, v44
	v_lshlrev_b64 v[44:45], 12, v[44:45]
	v_lshl_add_u64 v[44:45], v[34:35], 0, v[44:45]
	v_mov_b32_e32 v96, 0
	v_mov_b32_e32 v97, 0
	v_mov_b32_e32 v94, 0
	v_mov_b32_e32 v95, 0
	v_or_b32_e32 v38, s13, v7
	v_or_b32_e32 v40, s13, v6
	v_or_b32_e32 v42, s13, v9
	v_ashrrev_i32_e32 v43, 31, v42
	v_ashrrev_i32_e32 v41, 31, v40
	v_ashrrev_i32_e32 v39, 31, v38
	v_lshlrev_b64 v[38:39], 12, v[38:39]
	v_lshlrev_b64 v[40:41], 12, v[40:41]
	v_lshlrev_b64 v[42:43], 12, v[42:43]
	v_lshl_add_u64 v[42:43], v[34:35], 0, v[42:43]
	v_lshl_add_u64 v[40:41], v[34:35], 0, v[40:41]
	v_lshl_add_u64 v[38:39], v[34:35], 0, v[38:39]
	global_load_ushort v102, v[44:45], off offset:2048
	s_nop 0
	global_load_ushort v103, v[42:43], off offset:2048
	s_nop 0
	global_load_ushort v104, v[40:41], off offset:2048
	s_nop 0
	global_load_ushort v105, v[38:39], off offset:2048
	v_or_b32_e32 v44, s13, v12
	v_ashrrev_i32_e32 v45, 31, v44
	v_lshlrev_b64 v[44:45], 12, v[44:45]
	v_lshl_add_u64 v[44:45], v[34:35], 0, v[44:45]
	v_or_b32_e32 v38, s13, v11
	v_or_b32_e32 v40, s13, v10
	v_or_b32_e32 v42, s13, v13
	v_ashrrev_i32_e32 v43, 31, v42
	v_ashrrev_i32_e32 v41, 31, v40
	v_ashrrev_i32_e32 v39, 31, v38
	v_lshlrev_b64 v[38:39], 12, v[38:39]
	v_lshlrev_b64 v[40:41], 12, v[40:41]
	v_lshlrev_b64 v[42:43], 12, v[42:43]
	v_lshl_add_u64 v[42:43], v[34:35], 0, v[42:43]
	v_lshl_add_u64 v[40:41], v[34:35], 0, v[40:41]
	v_lshl_add_u64 v[38:39], v[34:35], 0, v[38:39]
	global_load_ushort v106, v[44:45], off offset:2048
	s_nop 0
	global_load_ushort v107, v[42:43], off offset:2048
	s_nop 0
	global_load_ushort v108, v[40:41], off offset:2048
	s_nop 0
	global_load_ushort v109, v[38:39], off offset:2048
	v_or_b32_e32 v44, s13, v16
	v_ashrrev_i32_e32 v45, 31, v44
	v_lshlrev_b64 v[44:45], 12, v[44:45]
	v_lshl_add_u64 v[44:45], v[34:35], 0, v[44:45]
	v_or_b32_e32 v38, s13, v15
	v_or_b32_e32 v40, s13, v14
	v_or_b32_e32 v42, s13, v17
	v_ashrrev_i32_e32 v43, 31, v42
	v_ashrrev_i32_e32 v41, 31, v40
	v_ashrrev_i32_e32 v39, 31, v38
	v_lshlrev_b64 v[38:39], 12, v[38:39]
	v_lshlrev_b64 v[40:41], 12, v[40:41]
	v_lshlrev_b64 v[42:43], 12, v[42:43]
	v_lshl_add_u64 v[42:43], v[34:35], 0, v[42:43]
	v_lshl_add_u64 v[40:41], v[34:35], 0, v[40:41]
	v_lshl_add_u64 v[38:39], v[34:35], 0, v[38:39]
	global_load_ushort v110, v[44:45], off offset:2048
	s_nop 0
	global_load_ushort v111, v[42:43], off offset:2048
	s_nop 0
	global_load_ushort v112, v[40:41], off offset:2048
	s_nop 0
; __device__ __forceinline__ void phase_hg_out(const Params& p, int l, char* smem) {
;     ...
;       const int d = tid & 127;
;       for (int idx = tid; idx < 64 * 128; idx += 256) {
;         const int s = idx >> 7;
;         VTs[d * 72 + s] = Uhg[(size_t)(t0 + s) * 2048 + 1024 + h * 128 + d];
;       }
;     }
;     __syncthreads();
;     ...
;     for (int ks = 0; ks < 4; ++ks) {
;       const int d0 = ks * 32 + q * 8;
;       const bf16x8 qraw = *(const bf16x8*)(Uhg + (size_t)(t0 + tt) * 2048 + h * 128 + d0);
	global_load_ushort v113, v[38:39], off offset:2048
	v_or_b32_e32 v38, s13, v19
	v_or_b32_e32 v40, s13, v18
	v_or_b32_e32 v42, s13, v21
	v_or_b32_e32 v44, s13, v20
	v_ashrrev_i32_e32 v45, 31, v44
	v_ashrrev_i32_e32 v43, 31, v42
	v_ashrrev_i32_e32 v41, 31, v40
	v_ashrrev_i32_e32 v39, 31, v38
	v_lshlrev_b64 v[38:39], 12, v[38:39]
	v_lshlrev_b64 v[40:41], 12, v[40:41]
	v_lshlrev_b64 v[42:43], 12, v[42:43]
	v_lshlrev_b64 v[44:45], 12, v[44:45]
	v_lshl_add_u64 v[44:45], v[34:35], 0, v[44:45]
	v_lshl_add_u64 v[42:43], v[34:35], 0, v[42:43]
	v_lshl_add_u64 v[40:41], v[34:35], 0, v[40:41]
	v_lshl_add_u64 v[38:39], v[34:35], 0, v[38:39]
	global_load_ushort v114, v[44:45], off offset:2048
	s_nop 0
	global_load_ushort v115, v[42:43], off offset:2048
	s_nop 0
	global_load_ushort v116, v[40:41], off offset:2048
	s_nop 0
	global_load_ushort v117, v[38:39], off offset:2048
	v_or_b32_e32 v38, s13, v23
	v_or_b32_e32 v40, s13, v22
	v_or_b32_e32 v42, s13, v25
	v_or_b32_e32 v44, s13, v24
	v_ashrrev_i32_e32 v45, 31, v44
	v_ashrrev_i32_e32 v43, 31, v42
	v_ashrrev_i32_e32 v41, 31, v40
	v_ashrrev_i32_e32 v39, 31, v38
	v_lshlrev_b64 v[38:39], 12, v[38:39]
	v_lshlrev_b64 v[40:41], 12, v[40:41]
	v_lshlrev_b64 v[42:43], 12, v[42:43]
	v_lshlrev_b64 v[44:45], 12, v[44:45]
	v_lshl_add_u64 v[44:45], v[34:35], 0, v[44:45]
	v_lshl_add_u64 v[42:43], v[34:35], 0, v[42:43]
	v_lshl_add_u64 v[40:41], v[34:35], 0, v[40:41]
	v_lshl_add_u64 v[38:39], v[34:35], 0, v[38:39]
	global_load_ushort v118, v[44:45], off offset:2048
	s_nop 0
	global_load_ushort v119, v[42:43], off offset:2048
	s_nop 0
	global_load_ushort v120, v[40:41], off offset:2048
	s_nop 0
	global_load_ushort v121, v[38:39], off offset:2048
	v_or_b32_e32 v38, s13, v27
	v_or_b32_e32 v40, s13, v26
	v_or_b32_e32 v42, s13, v29
	v_or_b32_e32 v44, s13, v28
	v_ashrrev_i32_e32 v45, 31, v44
	v_ashrrev_i32_e32 v43, 31, v42
	v_ashrrev_i32_e32 v41, 31, v40
	v_ashrrev_i32_e32 v39, 31, v38
	v_lshlrev_b64 v[38:39], 12, v[38:39]
	v_lshlrev_b64 v[40:41], 12, v[40:41]
	v_lshlrev_b64 v[42:43], 12, v[42:43]
	v_lshlrev_b64 v[44:45], 12, v[44:45]
	v_lshl_add_u64 v[44:45], v[34:35], 0, v[44:45]
	v_lshl_add_u64 v[42:43], v[34:35], 0, v[42:43]
	v_lshl_add_u64 v[40:41], v[34:35], 0, v[40:41]
	v_lshl_add_u64 v[38:39], v[34:35], 0, v[38:39]
	global_load_ushort v122, v[44:45], off offset:2048
	s_nop 0
	global_load_ushort v123, v[42:43], off offset:2048
	s_nop 0
	global_load_ushort v124, v[40:41], off offset:2048
	s_nop 0
	global_load_ushort v125, v[38:39], off offset:2048
	v_or_b32_e32 v38, s13, v31
	v_or_b32_e32 v40, s13, v30
	v_or_b32_e32 v42, s13, v33
	v_or_b32_e32 v44, s13, v32
	v_ashrrev_i32_e32 v45, 31, v44
	v_ashrrev_i32_e32 v43, 31, v42
	v_ashrrev_i32_e32 v41, 31, v40
	v_ashrrev_i32_e32 v39, 31, v38
	v_lshlrev_b64 v[38:39], 12, v[38:39]
	v_lshlrev_b64 v[40:41], 12, v[40:41]
	v_lshlrev_b64 v[42:43], 12, v[42:43]
	v_lshlrev_b64 v[44:45], 12, v[44:45]
	v_lshl_add_u64 v[44:45], v[34:35], 0, v[44:45]
	v_lshl_add_u64 v[42:43], v[34:35], 0, v[42:43]
	v_lshl_add_u64 v[40:41], v[34:35], 0, v[40:41]
	v_lshl_add_u64 v[34:35], v[34:35], 0, v[38:39]
	global_load_ushort v126, v[44:45], off offset:2048
	global_load_ushort v127, v[42:43], off offset:2048
	global_load_ushort v128, v[40:41], off offset:2048
	s_nop 0
	global_load_ushort v129, v[34:35], off offset:2048
	s_waitcnt vmcnt(0)
	ds_write_b16 v222, v98 offset:34304
	ds_write_b16 v223, v99 offset:34304
	ds_write_b16 v224, v100 offset:34304
	ds_write_b16 v225, v101 offset:34304
	ds_write_b16 v226, v102 offset:34304
	ds_write_b16 v227, v103 offset:34304
	ds_write_b16 v228, v104 offset:34304
	ds_write_b16 v229, v105 offset:34304
	ds_write_b16 v230, v106 offset:34304
	ds_write_b16 v231, v107 offset:34304
	ds_write_b16 v232, v108 offset:34304
	ds_write_b16 v233, v109 offset:34304
	ds_write_b16 v234, v110 offset:34304
	ds_write_b16 v235, v111 offset:34304
	ds_write_b16 v236, v112 offset:34304
	ds_write_b16 v237, v113 offset:34304
	ds_write_b16 v238, v114 offset:34304
	ds_write_b16 v239, v115 offset:34304
	ds_write_b16 v240, v116 offset:34304
	ds_write_b16 v241, v117 offset:34304
	ds_write_b16 v242, v118 offset:34304
	ds_write_b16 v243, v119 offset:34304
	ds_write_b16 v244, v120 offset:34304
	ds_write_b16 v245, v121 offset:34304
	ds_write_b16 v246, v122 offset:34304
	ds_write_b16 v247, v123 offset:34304
	ds_write_b16 v248, v124 offset:34304
	ds_write_b16 v249, v125 offset:34304
	ds_write_b16 v250, v126 offset:34304
	ds_write_b16 v251, v127 offset:34304
	ds_write_b16 v199, v128 offset:34304
	ds_write_b16 v200, v129 offset:34304
	v_mov_b32_e32 v37, 0
	v_mov_b32_e32 v34, 0
	v_mov_b32_e32 v35, 0
	v_or_b32_e32 v162, s13, v139
	v_ashrrev_i32_e32 v163, 31, v162
	v_readlane_b32 s0, v252, 46
	v_lshlrev_b64 v[38:39], 12, v[162:163]
	v_readlane_b32 s1, v252, 47
	v_lshl_add_u64 v[38:39], s[0:1], 0, v[38:39]
	v_lshl_add_u64 v[160:161], v[38:39], 0, s[58:59]
	v_lshl_add_u64 v[38:39], v[160:161], 0, v[0:1]
	global_load_dwordx4 v[98:101], v[38:39], off
	global_load_dwordx4 v[102:105], v[38:39], off offset:64
	global_load_dwordx4 v[106:109], v[38:39], off offset:128
	global_load_dwordx4 v[110:113], v[38:39], off offset:192
	s_waitcnt lgkmcnt(0)
	s_barrier
	s_and_saveexec_b64 s[0:1], s[50:51]
	s_cbranch_execz .LBB0_45
	ds_read_b128 v[94:97], v204 offset:16368
	ds_read_b128 v[34:37], v204 offset:16384

; __device__ __forceinline__ float bf2f(u16 h) { return __uint_as_float(((u32)h) << 16); }
; __device__ __forceinline__ float siluf_(float x) { return x / (1.0f + __expf(-x)); }
; __device__ __forceinline__ void phase_hg_out(const Params& p, int l, char* smem) {
;     ...
;     for (int ks = 0; ks < 4; ++ks) {
;       const int d0 = ks * 32 + q * 8;
;       const bf16x8 qraw = *(const bf16x8*)(Uhg + (size_t)(t0 + tt) * 2048 + h * 128 + d0);
;       float bt8[8];
;       load8f(bc + tt * BCS + d0, bt8);
;       uint4 wt, wh;
;       float a_[8], b_[8];
; #pragma unroll
;       for (int j = 0; j < 8; ++j) {
;         const float qv = siluf_(bf2f((u16)qraw[j]));
;         a_[j] = qv * __expf(bt8[j] - rr8[ks][j]);
;         b_[j] = qv * __expf(bt8[j]);
;       }
;       wt = pack8(a_); wh = pack8(b_);
;       Qt[ks] = __builtin_bit_cast(bf16x8, wt);
;       Qh[ks] = __builtin_bit_cast(bf16x8, wh);
;     }
;     f32x4 at[4];
; #pragma unroll
;     for (int st = 0; st < 4; ++st) {
;       at[st] = (f32x4){0.f, 0.f, 0.f, 0.f};
;       if (st <= wave) {
;         f32x4 a = {0.f, 0.f, 0.f, 0.f};
;         const int srow = st * 16 + c16;
; #pragma unroll
;         for (int ks = 0; ks < 4; ++ks) {
;           const int d0 = ks * 32 + q * 8;
;           float bs8[8], bp8[8], kv[8];
;           load8f(bc + srow * BCS + d0, bs8);
;           if (srow > 0) load8f(bc + (srow - 1) * BCS + d0, bp8);
.LBB0_51:
	s_or_b64 exec, exec, s[0:1]
	v_mov_b32_e32 v115, 0
	v_mov_b32_e32 v116, 0
	ds_read_b128 v[66:69], v205
	ds_read_b128 v[62:65], v205 offset:16
	ds_read_b128 v[58:61], v205 offset:128
	ds_read_b128 v[54:57], v205 offset:144
	ds_read_b128 v[50:53], v205 offset:256
	ds_read_b128 v[46:49], v205 offset:272
	ds_read_b128 v[42:45], v205 offset:384
	ds_read_b128 v[38:41], v205 offset:400
	ds_read_b128 v[126:129], v206
	ds_read_b128 v[118:121], v206 offset:16
	v_mov_b32_e32 v117, 0
	v_mov_b32_e32 v122, 0
	v_mov_b32_e32 v123, 0
	v_mov_b32_e32 v124, 0
	v_mov_b32_e32 v125, 0
	s_and_saveexec_b64 s[0:1], s[42:43]
	s_cbranch_execz .LBB0_53
	v_add_u32_e32 v122, 0xfffffdf0, v206
	ds_read_b128 v[114:117], v122
	ds_read_b128 v[122:125], v122 offset:16
